# XCD-local barriers: L1 invalidate issued with the arrival atomic instead of after the generation bump (leader and pollers), global path unchanged
# speedup vs baseline: 1.0062x; 1.0019x over previous
.LBB0_218:
	s_lshl_b32 s6, s3, 8
	s_mov_b32 s7, 0
	v_lshl_add_u64 v[2:3], v[0:1], 0, s[6:7]
	v_add_co_u32_e32 v8, vcc, 0x1000, v2
	v_mov_b32_e32 v5, 1
	s_nop 0
	v_addc_co_u32_e32 v9, vcc, 0, v3, vcc
	global_atomic_add v5, v[8:9], v5, off offset:1024 sc0
	v_readlane_b32 s98, v254, 2
	s_nop 0
	s_cmp_lg_u32 s98, 0
	s_cbranch_scc0 .Lei_a_1
	buffer_inv sc1
.Lei_a_1:
	v_cvt_f32_u32_e32 v7, v6
	v_sub_u32_e32 v8, 0, v6
	v_rcp_iflag_f32_e32 v7, v7
	s_nop 0
	v_mul_f32_e32 v7, 0x4f7ffffe, v7
	v_cvt_u32_f32_e32 v7, v7
	v_mul_lo_u32 v8, v8, v7
	v_mul_hi_u32 v8, v7, v8
	v_add_u32_e32 v7, v7, v8
	s_waitcnt vmcnt(0)
	v_mul_hi_u32 v7, v5, v7
	v_mul_lo_u32 v9, v7, v6
	v_add_u32_e32 v8, 1, v5
	v_sub_u32_e32 v5, v5, v9
	v_add_u32_e32 v10, 1, v7
	v_cmp_ge_u32_e32 vcc, v5, v6
	v_sub_u32_e32 v9, v5, v6
	s_nop 0
	v_cndmask_b32_e32 v7, v7, v10, vcc
	v_cndmask_b32_e32 v5, v5, v9, vcc
	v_add_u32_e32 v9, 1, v7
	v_cmp_ge_u32_e32 vcc, v5, v6
	s_nop 1
	v_cndmask_b32_e32 v5, v7, v9, vcc
	v_mad_u64_u32 v[6:7], s[6:7], v6, v5, v[6:7]
	v_cmp_ne_u32_e32 vcc, v8, v6
	s_and_saveexec_b64 s[6:7], vcc
	s_xor_b64 s[6:7], exec, s[6:7]
	s_cbranch_execz .LBB0_231
	v_add_co_u32_e32 v6, vcc, 0x2000, v2
	s_nop 1
	v_addc_co_u32_e32 v7, vcc, 0, v3, vcc
	s_waitcnt lgkmcnt(0)
	global_load_dword v4, v[6:7], off offset:1024 sc1
	s_waitcnt vmcnt(0)
	v_cmp_eq_u32_e32 vcc, v4, v5
	s_and_saveexec_b64 s[8:9], vcc
	s_cbranch_execz .LBB0_230
	s_mov_b64 s[10:11], 0x2400
	v_lshl_add_u64 v[2:3], v[2:3], 0, s[10:11]
	s_mov_b32 s3, 1
	s_mov_b64 s[10:11], 0
	s_branch .LBB0_222

.LBB0_230:
	s_or_b64 exec, exec, s[8:9]
	s_waitcnt vmcnt(0)
	v_readlane_b32 s98, v254, 2
	s_nop 0
	s_cmp_lg_u32 s98, 0
	s_cbranch_scc1 .Lei_b_1
	buffer_inv sc1
	s_waitcnt vmcnt(0)
.Lei_b_1:
.LBB0_231:
	s_andn2_saveexec_b64 s[6:7], s[6:7]
	s_cbranch_execz .LBB0_247
	v_readlane_b32 s98, v254, 2
	s_nop 0
	s_cmp_lg_u32 s98, 0
	s_cbranch_scc1 .Llb_fast_1
	v_add_co_u32_e32 v6, vcc, 0x3000, v0
	buffer_wbl2 sc1
	s_waitcnt lgkmcnt(0)
	s_waitcnt vmcnt(0)
	v_addc_co_u32_e32 v7, vcc, 0, v1, vcc
	v_mov_b32_e32 v5, 1
	global_atomic_add v5, v[6:7], v5, off offset:1024 sc0
	v_cvt_f32_u32_e32 v6, v4
	v_sub_u32_e32 v8, 0, v4
	s_mov_b64 s[6:7], 0x3500
	s_mov_b64 s[8:9], -1
	v_rcp_iflag_f32_e32 v6, v6
	s_nop 0
	v_mul_f32_e32 v6, 0x4f7ffffe, v6
	v_cvt_u32_f32_e32 v9, v6
	v_lshl_add_u64 v[6:7], v[0:1], 0, s[6:7]
	v_mul_lo_u32 v8, v8, v9
	v_mul_hi_u32 v8, v9, v8
	v_add_u32_e32 v8, v9, v8
	s_waitcnt vmcnt(0)
	v_mul_hi_u32 v8, v5, v8
	v_mul_lo_u32 v10, v8, v4
	v_add_u32_e32 v9, 1, v5
	v_sub_u32_e32 v5, v5, v10
	v_add_u32_e32 v11, 1, v8
	v_cmp_ge_u32_e32 vcc, v5, v4
	v_sub_u32_e32 v10, v5, v4
	s_nop 0
	v_cndmask_b32_e32 v8, v8, v11, vcc
	v_cndmask_b32_e32 v5, v5, v10, vcc
	v_add_u32_e32 v10, 1, v8
	v_cmp_ge_u32_e32 vcc, v5, v4
	s_nop 1
	v_cndmask_b32_e32 v8, v8, v10, vcc
	v_mad_u64_u32 v[4:5], s[6:7], v4, v8, v[4:5]
	v_cmp_ne_u32_e32 vcc, v9, v4
	s_and_saveexec_b64 s[6:7], vcc
	s_cbranch_execz .LBB0_244
	global_load_dword v4, v[6:7], off sc1
	s_mov_b64 s[10:11], 0
	s_waitcnt vmcnt(0)
	v_cmp_eq_u32_e32 vcc, v4, v8
	s_and_saveexec_b64 s[8:9], vcc
	s_cbranch_execz .LBB0_243
	s_mov_b64 s[10:11], 0x200
	v_lshl_add_u64 v[4:5], v[0:1], 0, s[10:11]
	s_mov_b32 s3, 1
	s_mov_b64 s[10:11], 0
	s_branch .LBB0_236

.Llb_fast_1:
	v_add_co_u32_e32 v0, vcc, 0x2000, v2
	v_mov_b32_e32 v2, 1
	s_nop 0
	v_addc_co_u32_e32 v1, vcc, 0, v3, vcc
	s_waitcnt vmcnt(0)
	v_readlane_b32 s98, v254, 2
	s_nop 0
	s_cmp_lg_u32 s98, 0
	s_cbranch_scc1 .Lei_c_1
	buffer_inv sc1
.Lei_c_1:
	global_atomic_add v[0:1], v2, off offset:1024
	s_waitcnt vmcnt(0)

.LBB0_644:
	s_lshl_b32 s8, s3, 8
	s_mov_b32 s9, 0
	v_lshl_add_u64 v[2:3], v[0:1], 0, s[8:9]
	v_add_co_u32_e32 v8, vcc, 0x1000, v2
	v_mov_b32_e32 v5, 1
	s_nop 0
	v_addc_co_u32_e32 v9, vcc, 0, v3, vcc
	global_atomic_add v5, v[8:9], v5, off offset:1024 sc0
	v_readlane_b32 s98, v254, 2
	s_nop 0
	s_cmp_lg_u32 s98, 0
	s_cbranch_scc0 .Lei_a_6
	buffer_inv sc1
.Lei_a_6:
	v_cvt_f32_u32_e32 v7, v6
	v_sub_u32_e32 v8, 0, v6
	v_rcp_iflag_f32_e32 v7, v7
	s_nop 0
	v_mul_f32_e32 v7, 0x4f7ffffe, v7
	v_cvt_u32_f32_e32 v7, v7
	v_mul_lo_u32 v8, v8, v7
	v_mul_hi_u32 v8, v7, v8
	v_add_u32_e32 v7, v7, v8
	s_waitcnt vmcnt(0)
	v_mul_hi_u32 v7, v5, v7
	v_mul_lo_u32 v9, v7, v6
	v_add_u32_e32 v8, 1, v5
	v_sub_u32_e32 v5, v5, v9
	v_add_u32_e32 v10, 1, v7
	v_cmp_ge_u32_e32 vcc, v5, v6
	v_sub_u32_e32 v9, v5, v6
	s_nop 0
	v_cndmask_b32_e32 v7, v7, v10, vcc
	v_cndmask_b32_e32 v5, v5, v9, vcc
	v_add_u32_e32 v9, 1, v7
	v_cmp_ge_u32_e32 vcc, v5, v6
	s_nop 1
	v_cndmask_b32_e32 v5, v7, v9, vcc
	v_mad_u64_u32 v[6:7], s[8:9], v6, v5, v[6:7]
	v_cmp_ne_u32_e32 vcc, v8, v6
	s_and_saveexec_b64 s[8:9], vcc
	s_xor_b64 s[8:9], exec, s[8:9]
	s_cbranch_execz .LBB0_657
	v_add_co_u32_e32 v6, vcc, 0x2000, v2
	s_nop 1
	v_addc_co_u32_e32 v7, vcc, 0, v3, vcc
	s_waitcnt lgkmcnt(0)
	global_load_dword v4, v[6:7], off offset:1024 sc1
	s_waitcnt vmcnt(0)
	v_cmp_eq_u32_e32 vcc, v4, v5
	s_and_saveexec_b64 s[10:11], vcc
	s_cbranch_execz .LBB0_656
	s_mov_b64 s[12:13], 0x2400
	v_lshl_add_u64 v[2:3], v[2:3], 0, s[12:13]
	s_mov_b32 s3, 1
	s_mov_b64 s[12:13], 0
	s_branch .LBB0_648

.LBB0_656:
	s_or_b64 exec, exec, s[10:11]
	s_waitcnt vmcnt(0)
	v_readlane_b32 s98, v254, 2
	s_nop 0
	s_cmp_lg_u32 s98, 0
	s_cbranch_scc1 .Lei_b_6
	buffer_inv sc1
	s_waitcnt vmcnt(0)
.Lei_b_6:
.LBB0_657:
	s_andn2_saveexec_b64 s[8:9], s[8:9]
	s_cbranch_execz .LBB0_673
	v_readlane_b32 s98, v254, 2
	s_nop 0
	s_cmp_lg_u32 s98, 0
	s_cbranch_scc1 .Llb_fast_6
	v_add_co_u32_e32 v6, vcc, 0x3000, v0
	buffer_wbl2 sc1
	s_waitcnt lgkmcnt(0)
	s_waitcnt vmcnt(0)
	v_addc_co_u32_e32 v7, vcc, 0, v1, vcc
	v_mov_b32_e32 v5, 1
	global_atomic_add v5, v[6:7], v5, off offset:1024 sc0
	v_cvt_f32_u32_e32 v6, v4
	v_sub_u32_e32 v8, 0, v4
	s_mov_b64 s[8:9], 0x3500
	s_mov_b64 s[10:11], -1
	v_rcp_iflag_f32_e32 v6, v6
	s_nop 0
	v_mul_f32_e32 v6, 0x4f7ffffe, v6
	v_cvt_u32_f32_e32 v9, v6
	v_lshl_add_u64 v[6:7], v[0:1], 0, s[8:9]
	v_mul_lo_u32 v8, v8, v9
	v_mul_hi_u32 v8, v9, v8
	v_add_u32_e32 v8, v9, v8
	s_waitcnt vmcnt(0)
	v_mul_hi_u32 v8, v5, v8
	v_mul_lo_u32 v10, v8, v4
	v_add_u32_e32 v9, 1, v5
	v_sub_u32_e32 v5, v5, v10
	v_add_u32_e32 v11, 1, v8
	v_cmp_ge_u32_e32 vcc, v5, v4
	v_sub_u32_e32 v10, v5, v4
	s_nop 0
	v_cndmask_b32_e32 v8, v8, v11, vcc
	v_cndmask_b32_e32 v5, v5, v10, vcc
	v_add_u32_e32 v10, 1, v8
	v_cmp_ge_u32_e32 vcc, v5, v4
	s_nop 1
	v_cndmask_b32_e32 v8, v8, v10, vcc
	v_mad_u64_u32 v[4:5], s[8:9], v4, v8, v[4:5]
	v_cmp_ne_u32_e32 vcc, v9, v4
	s_and_saveexec_b64 s[8:9], vcc
	s_cbranch_execz .LBB0_670
	global_load_dword v4, v[6:7], off sc1
	s_mov_b64 s[12:13], 0
	s_waitcnt vmcnt(0)
	v_cmp_eq_u32_e32 vcc, v4, v8
	s_and_saveexec_b64 s[10:11], vcc
	s_cbranch_execz .LBB0_669
	s_mov_b64 s[12:13], 0x200
	v_lshl_add_u64 v[4:5], v[0:1], 0, s[12:13]
	s_mov_b32 s3, 1
	s_mov_b64 s[12:13], 0
	s_branch .LBB0_662
